# v12 + attention work remap: the 16 workgroups that stream the same (batch, head) K/V are co-located on one XCD (virtual block id = (BID&7)*32 + BID/8), same work per workgroup
# speedup vs baseline: 1.0331x; 1.0079x over previous
.LBB0_39:
	v_readlane_b32 s10, v243, 29
	v_readlane_b32 s11, v243, 30
	s_add_u32 s0, s10, 0xb471000
	v_writelane_b32 v243, s0, 36
	s_addc_u32 s0, s11, 0
	v_writelane_b32 v243, s0, 37
	s_add_u32 s0, s10, 0x28271000
	v_lshrrev_b32_e32 v201, 5, v0
	v_lshrrev_b32_e32 v1, 1, v186
	v_writelane_b32 v243, s0, 38
	s_addc_u32 s0, s11, 0
	v_and_b32_e32 v187, 31, v186
	v_bitop3_b32 v1, v201, v1, 7 bitop3:0x78
	v_writelane_b32 v243, s0, 39
	s_add_u32 s0, s10, 0x1fc71000
	v_bfe_u32 v2, v186, 1, 3
	v_mul_u32_u24_e32 v3, 0x180, v187
	v_lshlrev_b32_e32 v4, 7, v187
	v_lshlrev_b32_e32 v1, 4, v1
	v_writelane_b32 v243, s0, 40
	s_addc_u32 s0, s11, 0
	v_or_b32_e32 v202, v1, v3
	v_or_b32_e32 v203, v1, v4
	v_bitop3_b32 v1, v201, v2, 2 bitop3:0x36
	v_writelane_b32 v243, s0, 41
	s_add_u32 s0, s10, 0x30271000
	v_lshlrev_b32_e32 v1, 4, v1
	v_writelane_b32 v243, s0, 42
	s_addc_u32 s0, s11, 0
	v_or_b32_e32 v204, v1, v3
	v_or_b32_e32 v205, v1, v4
	v_bitop3_b32 v1, v201, v2, 4 bitop3:0x36
	s_add_u32 s80, s10, 0x20271000
	v_lshlrev_b32_e32 v1, 4, v1
	s_addc_u32 s81, s11, 0
	v_or_b32_e32 v206, v1, v3
	v_or_b32_e32 v207, v1, v4
	v_bitop3_b32 v1, v201, v2, 6 bitop3:0x36
	v_writelane_b32 v243, s0, 43
	s_add_u32 s78, s10, 0x17471000
	v_lshlrev_b32_e32 v1, 4, v1
	s_addc_u32 s79, s11, 0
	v_readlane_b32 s0, v243, 34
	v_or_b32_e32 v208, v1, v3
	v_or_b32_e32 v209, v1, v4
	s_cmp_eq_u32 s0, 13
	v_readlane_b32 s12, v244, 33
	v_lshl_or_b32 v1, s94, 7, v0
	v_readlane_b32 s1, v243, 35
	s_cselect_b32 s0, 0, 0x200
	v_readlane_b32 s24, v244, 45
	v_or_b32_e32 v2, 64, v1
	s_cselect_b32 s1, 0, 0x100
	v_readlane_b32 s13, v244, 34
	v_readlane_b32 s25, v244, 46
	s_add_u32 s12, s24, s0
	v_lshrrev_b32_e32 v3, 4, v2
	v_readlane_b32 s26, v244, 47
	s_addc_u32 s13, s25, 0
	v_xor_b32_e32 v3, v3, v186
	v_lshlrev_b32_e32 v2, 12, v2
	v_readlane_b32 s27, v244, 48
	v_writelane_b32 v243, s12, 44
	s_add_u32 s0, s26, s1
	v_lshlrev_b32_e32 v3, 3, v3
	v_and_b32_e32 v2, 0xffff8000, v2
	v_lshrrev_b32_e32 v0, 4, v0
	v_writelane_b32 v243, s13, 45
	s_addc_u32 s1, s27, 0
	v_and_or_b32 v192, v3, 56, v2
	v_xor_b32_e32 v2, v0, v186
	v_writelane_b32 v243, s0, 46
	v_lshlrev_b32_e32 v2, 3, v2
	v_and_b32_e32 v2, 56, v2
	v_writelane_b32 v243, s1, 47
	v_lshlrev_b32_e32 v1, 12, v1
	s_mov_b32 s0, 0xfffb8000
	v_and_or_b32 v194, v1, s0, v2
	s_lshl_b32 s0, s94, 11
	s_lshl_b32 s1, s94, 5
	s_add_i32 s33, s0, 0
	s_mul_i32 s0, s94, 0x4200
	v_lshlrev_b32_e32 v1, 3, v186
	s_ashr_i32 s97, s2, 7
	s_add_i32 s2, s0, 0
	v_and_b32_e32 v210, 0x78, v1
	v_lshlrev_b32_e32 v1, 2, v201
	v_or_b32_e32 v2, s1, v187
	s_add_i32 s96, s33, 0x12000
	v_writelane_b32 v243, s2, 48
	s_lshl_b32 s95, s3, 10
	s_lshl_b32 s86, s8, 10
	v_sub_u32_e32 v211, v2, v1
	v_lshlrev_b32_e32 v1, 7, v186
	v_writelane_b32 v243, s1, 49
	s_add_u32 s1, s10, 0x1fc77000
	v_and_b32_e32 v196, 0x1800, v1
	v_mov_b32_e32 v1, s0
	s_movk_i32 s0, 0x210
	v_writelane_b32 v243, s1, 50
	s_addc_u32 s1, s11, 0
	v_mad_u32_u24 v0, v0, s0, v1
	v_and_b32_e32 v1, 15, v186
	v_writelane_b32 v243, s1, 51
	v_lshlrev_b32_e32 v1, 5, v1
	s_mulk_i32 s94, 0xc00
	v_mov_b32_e32 v189, v185
	v_mov_b32_e32 v191, v185
	v_mov_b32_e32 v195, v185
	v_mov_b32_e32 v193, v185
	v_mov_b32_e32 v197, v185
	v_add3_u32 v212, v0, v1, 0
	v_readlane_b32 s0, v243, 31
	s_and_b32 s14, s0, 7
	s_lshl_b32 s14, s14, 5
	s_lshr_b32 s0, s0, 3
	s_or_b32 s0, s0, s14
	v_writelane_b32 v243, s74, 52
	v_readlane_b32 s14, v244, 35
	v_readlane_b32 s15, v244, 36
	v_readlane_b32 s16, v244, 37
	v_readlane_b32 s17, v244, 38
	v_readlane_b32 s18, v244, 39
	v_readlane_b32 s19, v244, 40
	v_readlane_b32 s20, v244, 41
	v_readlane_b32 s21, v244, 42
	v_readlane_b32 s22, v244, 43
	v_readlane_b32 s23, v244, 44
	v_writelane_b32 v243, s75, 53
